# v009 plus: differential attention issues the next step's K staging loads behind the step's first eight LDS reads instead of between the step barrier and them
# baseline (speedup 1.0000x reference)
.LBB0_376:
.LBB0_377:
	s_mul_i32 s14, s48, 0x8800
	v_add_u32_e32 v6, s14, v193
	s_setprio 1
	ds_read_b128 v[2:5], v6
	ds_read_b128 v[112:115], v6 offset:32
	ds_read_b128 v[116:119], v6 offset:64
	ds_read_b128 v[120:123], v6 offset:96
	ds_read_b128 v[124:127], v6 offset:8704
	ds_read_b128 v[128:131], v6 offset:8736
	ds_read_b128 v[132:135], v6 offset:8768
	ds_read_b128 v[136:139], v6 offset:8800
	s_and_b64 vcc, exec, s[12:13]
	s_cbranch_vccz .Ldiff_nopf
	v_lshl_add_u64 v[8:9], v[178:179], 0, s[18:19]
	v_add_co_u32_e32 v10, vcc, 0x28010000, v8
	s_nop 1
	v_addc_co_u32_e32 v11, vcc, 0, v9, vcc
	v_add_co_u32_e32 v12, vcc, 0x28014000, v8
	s_nop 1
	v_addc_co_u32_e32 v13, vcc, 0, v9, vcc
	s_waitcnt vmcnt(0)
	global_load_dwordx4 v[160:163], v[10:11], off
	global_load_dwordx4 v[164:167], v[12:13], off
	v_add_co_u32_e32 v10, vcc, 0x28018000, v8
	s_nop 1
	v_addc_co_u32_e32 v11, vcc, 0, v9, vcc
	v_add_co_u32_e32 v8, vcc, 0x2801c000, v8
	s_nop 1
	v_addc_co_u32_e32 v9, vcc, 0, v9, vcc
	global_load_dwordx4 v[168:171], v[10:11], off
	global_load_dwordx4 v[172:175], v[8:9], off
.Ldiff_nopf:
	s_waitcnt lgkmcnt(7)
	v_mfma_f32_32x32x16_bf16 v[96:111], v[2:5], v[156:159], 0
	s_waitcnt lgkmcnt(6)
	v_mfma_f32_32x32x16_bf16 v[96:111], v[112:115], v[152:155], v[96:111]
	s_waitcnt lgkmcnt(5)
	v_mfma_f32_32x32x16_bf16 v[96:111], v[116:119], v[148:151], v[96:111]
	s_waitcnt lgkmcnt(4)
	v_mfma_f32_32x32x16_bf16 v[96:111], v[120:123], v[144:147], v[96:111]
	s_waitcnt lgkmcnt(3)
	v_mfma_f32_32x32x16_bf16 v[80:95], v[124:127], v[156:159], 0
	s_waitcnt lgkmcnt(2)
	v_mfma_f32_32x32x16_bf16 v[80:95], v[128:131], v[152:155], v[80:95]
	s_waitcnt lgkmcnt(1)
	v_mfma_f32_32x32x16_bf16 v[80:95], v[132:135], v[148:151], v[80:95]
	s_waitcnt lgkmcnt(0)
	v_mfma_f32_32x32x16_bf16 v[80:95], v[136:139], v[144:147], v[80:95]
	s_setprio 0
	s_sub_i32 s14, s50, 64
	s_cmp_le_u32 s14, s47
	s_cbranch_scc0 .LBB0_379
	v_mov_b32_e32 v0, s49
	ds_read_b32 v182, v0 offset:512
	s_mov_b64 s[14:15], 0
	s_branch .LBB0_380
